# speedup vs baseline: 1.0362x; 1.0093x over previous
; __global__ void __launch_bounds__(NTHR, 2) hymba_fwd(Args args) {
;     ...
;     for (int ph = lo; ph < hi; ++ph) {
;         int l = ph / NPH; const int k = ph % NPH;
;         if (k == 3 || k == 11) continue;
;         asm volatile("" : "+s"(l));
;         int G = gridDim.x, bid = blockIdx.x; asm volatile("" : "+s"(G), "+s"(bid));
;     ...
;             for (int it = gw; it < NITEMS; it += NGW) {
;                 int r = it;
;                 if (r < I_UP) { transpose_item(L.ffn1_w1, D, FF, W13A, 1, scr, r, lane); continue; } r -= I_UP;
;                 if (r < I_UP) { transpose_item(L.ffn1_w3, D, FF, W13A, 2, scr, r, lane); continue; } r -= I_UP;
;                 if (r < I_DN) { transpose_item(L.ffn1_w2, FF, D, W2A, 0, scr, r, lane); continue; } r -= I_DN;
;                 if (r < I_IN) { transpose_item(L.w_in, D, DIN, WIN, 0, scr, r, lane); continue; } r -= I_IN;
;                 if (r < I_OUT) { transpose_item(L.w_out, D, D, WOUT, 0, scr, r, lane); continue; } r -= I_OUT;
;                 if (r < I_UP) { transpose_item(L.ffn2_w1, D, FF, W13B, 1, scr, r, lane); continue; } r -= I_UP;
;                 if (r < I_UP) { transpose_item(L.ffn2_w3, D, FF, W13B, 2, scr, r, lane); continue; } r -= I_UP;
;                 if (r < I_DN) { transpose_item(L.ffn2_w2, FF, D, W2B, 0, scr, r, lane); continue; } r -= I_DN;
;                 transpose_item(L.s5_gw, GW, GW, WGLU, 0, scr, r, lane);
;             }
.LBB0_20:
	s_lshr_b32 s5, s54, 1
	s_mul_hi_i32 s0, s5, 0x92492493
	s_add_i32 s0, s0, s5
	s_lshr_b32 s1, s0, 31
	s_ashr_i32 s0, s0, 3
	s_add_i32 s4, s0, s1
	s_mul_i32 s0, s4, 14
	s_sub_i32 s5, s5, s0
	s_cmp_eq_u32 s5, 1
	s_cselect_b32 s0, 1, 0
	s_cmp_eq_u32 s5, 4
	s_cselect_b32 s1, 1, 0
	s_or_b32 s0, s0, s1
	s_cmp_eq_u32 s5, 12
	s_cselect_b32 s1, 1, 0
	s_cmp_eq_u32 s4, 0
	s_cselect_b32 s1, s1, 0
	s_or_b32 s0, s0, s1
	s_bitcmp1_b32 s54, 0
	s_cbranch_scc1 .Lhdr_rep1
	s_cmp_eq_u32 s5, 0
	s_cselect_b32 s1, 1, 0
	s_cmp_eq_u32 s4, 1
	s_cselect_b32 s1, s1, 0
	s_or_b32 s0, s0, s1
	v_writelane_b32 v255, s0, 62
	s_mov_b32 s0, 0
	s_mov_b32 s1, 0xa07f
	v_writelane_b32 v255, s0, 61
	v_writelane_b32 v255, s1, 59
	s_movk_i32 s0, 0x2c00
	s_cmp_eq_u32 s4, 0
	s_cselect_b32 s0, s0, 0
	s_mov_b32 s1, 0x9fff
	v_writelane_b32 v255, s0, 57
	v_writelane_b32 v255, s1, 56
	s_branch .Lhdr_common
.Lhdr_rep1:
	s_cmp_eq_u32 s0, 0
	s_mov_b64 s[0:1], -1
	s_cbranch_scc1 .LBB0_24
	s_mov_b32 s0, 0x5600
	s_mov_b32 s1, 0x73ff
	s_cmp_eq_u32 s5, 1
	s_cmov_b32 s0, 0x2c00
	s_cmov_b32 s1, 0x55ff
	s_cmp_eq_u32 s5, 12
	s_cmov_b32 s0, 0
	s_cmov_b32 s1, 0x2bff
	s_cmp_eq_u32 s5, 7
	s_cmov_b32 s0, 0x8000
	s_cmov_b32 s1, 0x9fff
	v_writelane_b32 v255, s0, 60
	v_writelane_b32 v255, s1, 59
	s_mov_b32 s0, 0x80
	s_cmov_b32 s0, 64
	s_mov_b32 s1, 1
	v_writelane_b32 v255, s0, 58
	v_writelane_b32 v255, s1, 61
	s_mov_b32 s0, 0
	s_mov_b32 s1, 0x7fffffff
	v_writelane_b32 v255, s0, 62
	v_writelane_b32 v255, s1, 57
	v_writelane_b32 v255, s0, 56
	s_cmp_eq_u32 s5, 12
	s_addc_u32 s4, s4, 0
	s_mov_b32 s5, 0

; __device__ __forceinline__ void group_norm_rows(const float* Y, const float* RW, const LayerP& L, bf16* dst, int gw, int NGW, int lane) {
;     for (int m = gw; m < T; m += NGW) {
; #pragma unroll
;         for (int gi = 0; gi < 4; ++gi) {
;             const float* yr = Y + (size_t)m * D + gi * GW;
;             f32x4 a = ((const f32x4*)yr)[lane], b = ((const f32x4*)yr)[64 + lane];
;             if (gi == 2) {
;                 const int ca = 4 * lane, cb = 256 + 4 * lane;
;                 const float ma = row16_sum((a.x + a.y) + (a.z + a.w)) * (1.f / 64.f), mb = row16_sum((b.x + b.y) + (b.z + b.w)) * (1.f / 64.f);
;                 const f32x4 da = a - ma, db = b - mb;
;                 const float ra = rsqrtf(row16_sum(dot4(da, da)) * (1.f / 64.f) + 64e-5f), rb = rsqrtf(row16_sum(dot4(db, db)) * (1.f / 64.f) + 64e-5f);
;                 const f32x4 ga = *(const f32x4*)(L.rw_lng + ca), gb = *(const f32x4*)(L.rw_lng + cb), ba = *(const f32x4*)(L.rw_lnb + ca), bb = *(const f32x4*)(L.rw_lnb + cb);
;                 const f32x4 bna = *(const f32x4*)(RW + 7 * RWSZ + (size_t)m * GW + ca), bnb = *(const f32x4*)(RW + 7 * RWSZ + (size_t)m * GW + cb);
;                 const f32x4 gga = *(const f32x4*)(RW + 6 * RWSZ + (size_t)m * GW + ca), ggb = *(const f32x4*)(RW + 6 * RWSZ + (size_t)m * GW + cb);
;                 a = (da * ra * ga + ba + bna) * gga; b = (db * rb * gb + bb + bnb) * ggb;
;             }
;             const float ss = wave_sum(dot4(a, a) + dot4(b, b));
;             const float rstd = rsqrtf(ss * (1.f / GW) + 1e-6f);
;             const f32x4 na = ((const f32x4*)(L.out_norm + gi * GW))[lane], nb = ((const f32x4*)(L.out_norm + gi * GW))[64 + lane];
;             const f32x4 oa = a * rstd * na, ob = b * rstd * nb;
;             u32x2 w; w.x = pg8::cvt_pk_bf16(oa.x, oa.y); w.y = pg8::cvt_pk_bf16(oa.z, oa.w); ((u32x2*)(dst + (size_t)m * D + gi * GW))[lane] = w;
;             w.x = pg8::cvt_pk_bf16(ob.x, ob.y); w.y = pg8::cvt_pk_bf16(ob.z, ob.w); ((u32x2*)(dst + (size_t)m * D + gi * GW))[64 + lane] = w;
;         }
;     }
; }
; __global__ void __launch_bounds__(NTHR, 2) hymba_fwd(Args args) {
;     ...
;             for (int it = gw; it < NITEMS; it += NGW) {
;                 int r = it;
;                 if (r < I_UP) { transpose_item(L.ffn1_w1, D, FF, W13A, 1, scr, r, lane); continue; } r -= I_UP;
.Lgs_nobar:
	s_addk_i32 s30, 0x400
	s_cmpk_gt_i32 s30, 0x1fff
	s_cbranch_scc0 .Lgs_row
	v_readlane_b32 s0, v254, 44
	v_readlane_b32 s1, v254, 39
	s_sub_i32 s0, s0, 4
	s_lshl_b32 s1, s1, 2
	s_add_i32 s0, s0, s1
	s_add_i32 s0, s0, 0x7400
	s_movk_i32 s1, 0x400
	v_writelane_b32 v254, s0, 40
	v_writelane_b32 v254, s1, 42
	s_mov_b32 s0, 0x9fff
	s_mov_b32 s1, 0x7fffffff
	v_writelane_b32 v255, s0, 59
	v_writelane_b32 v255, s1, 57
	s_mov_b32 s0, 0
	s_mov_b32 s1, 2
	v_writelane_b32 v255, s0, 56
	v_writelane_b32 v255, s1, 61
	v_writelane_b32 v255, s28, 55
	s_waitcnt vmcnt(0)
	s_branch .Lp0_norm
.Lgs_drain:
	v_readlane_b32 s28, v255, 55

; __global__ void __launch_bounds__(NTHR, 2) hymba_fwd(Args args) {
;     ...
;         dupdone = false;
;     ...
;         if (ph + 1 < hi) xcd_barrier(xbar);
.Lgs_done:
	s_mov_b32 s0, 0
	s_nop 0
	v_writelane_b32 v255, s0, 61
	s_branch .LBB0_90

; __device__ __forceinline__ unsigned cvt_pk_bf16(float lo, float hi) { unsigned r; asm volatile("v_cvt_pk_bf16_f32 %0, %1, %2" : "=v"(r) : "v"(lo), "v"(hi)); return r; }
;     __device__ __forceinline__ void operator()(const f32x4 (&acc)[2][2][4][2], const Unit& u, int wr, int wc, int fr, int fq) const {
;     ...
;             for (int m = 0; m < 4; ++m) { const int row = u.pm * BM + ai * HALF + wr * 64 + m * 16 + fr; const size_t off = (size_t)row * ldc + col0;
;                 float ssum = 0.f;
; #pragma unroll
;                 for (int bj = 0; bj < 2; ++bj)
; #pragma unroll
;                     for (int n = 0; n < 2; ++n) { f32x4* p = (f32x4*)(X + off + bj * HALF + n * 16); const f32x4 v = *(const f32x4*)(Xin + off + bj * HALF + n * 16) + acc[ai][bj][m][n] * scale; *p = v;
;                         if (gnext) { ssum += (v.x * v.x + v.y * v.y) + (v.z * v.z + v.w * v.w); const f32x4 o = v * gv[bj][n];
;                             u32x2 w; w.x = cvt_pk_bf16(o.x, o.y); w.y = cvt_pk_bf16(o.z, o.w); *(u32x2*)(XB + off + bj * HALF + n * 16) = w; } }
;                 if (gnext) { ssum += __shfl_xor(ssum, 16); ssum += __shfl_xor(ssum, 32); if (fq == 0) unsafeAtomicAdd(SS + row, ssum); } }
.LBB0_502:
	v_lshl_add_u32 v162, s61, 8, v145
	v_ashrrev_i32_e32 v163, 31, v162
	v_add_u32_e32 v194, 0x0, v162
	v_ashrrev_i32_e32 v195, 31, v194
	v_lshlrev_b64 v[194:195], 11, v[194:195]
	v_lshl_add_u64 v[194:195], v[194:195], 0, v[164:165]
	v_lshlrev_b64 v[194:195], 2, v[194:195]
	v_lshl_add_u64 v[194:195], s[6:7], 0, v[194:195]
	global_load_dwordx4 v[200:203], v[194:195], off
	global_load_dwordx4 v[204:207], v[194:195], off offset:64
	global_load_dwordx4 v[208:211], v[194:195], off offset:512
	global_load_dwordx4 v[212:215], v[194:195], off offset:576
	v_add_u32_e32 v196, 0x10, v162
	v_ashrrev_i32_e32 v197, 31, v196
	v_lshlrev_b64 v[196:197], 11, v[196:197]
	v_lshl_add_u64 v[196:197], v[196:197], 0, v[164:165]
	v_lshlrev_b64 v[196:197], 2, v[196:197]
	v_lshl_add_u64 v[196:197], s[6:7], 0, v[196:197]
	global_load_dwordx4 v[216:219], v[196:197], off
	global_load_dwordx4 v[220:223], v[196:197], off offset:64
	global_load_dwordx4 v[224:227], v[196:197], off offset:512
	global_load_dwordx4 v[228:231], v[196:197], off offset:576
	v_add_u32_e32 v198, 0x20, v162
	v_ashrrev_i32_e32 v199, 31, v198
	v_lshlrev_b64 v[198:199], 11, v[198:199]
	v_lshl_add_u64 v[198:199], v[198:199], 0, v[164:165]
	v_lshlrev_b64 v[198:199], 2, v[198:199]
	v_lshl_add_u64 v[198:199], s[6:7], 0, v[198:199]
	global_load_dwordx4 v[232:235], v[198:199], off
	global_load_dwordx4 v[236:239], v[198:199], off offset:64
	global_load_dwordx4 v[240:243], v[198:199], off offset:512
	global_load_dwordx4 v[244:247], v[198:199], off offset:576
	s_waitcnt vmcnt(0)
	v_lshlrev_b64 v[166:167], 11, v[162:163]
	v_lshl_add_u64 v[170:171], v[166:167], 0, v[164:165]
	v_lshlrev_b64 v[166:167], 2, v[170:171]
	v_lshl_add_u64 v[168:169], s[6:7], 0, v[166:167]
	s_nop 1
	v_mov_b64_e32 v[190:191], v[200:201]
	v_mov_b64_e32 v[192:193], v[202:203]
	v_mov_b32_e32 v155, v154
	v_lshl_add_u64 v[166:167], s[16:17], 0, v[166:167]
	s_and_b64 vcc, exec, s[42:43]
	v_pk_fma_f32 v[142:143], v[154:155], v[142:143], v[192:193]
	v_pk_fma_f32 v[140:141], v[156:157], v[140:141], v[190:191]
	global_store_dwordx4 v[166:167], v[140:143], off
	s_cbranch_vccnz .LBB0_545
	v_mul_f32_e32 v180, v141, v141
	v_fmac_f32_e32 v180, v140, v140
	v_mul_f32_e32 v181, v143, v143
	v_pk_mul_f32 v[140:141], v[56:57], v[140:141]
	v_lshl_add_u64 v[170:171], v[170:171], 1, s[10:11]
	v_fmac_f32_e32 v181, v142, v142
	v_pk_mul_f32 v[142:143], v[58:59], v[142:143]
	v_cvt_pk_bf16_f32 v140, v140, v141
	v_add_f32_e32 v180, v180, v181
	v_cvt_pk_bf16_f32 v141, v142, v143
	global_store_dwordx2 v[170:171], v[140:141], off
	s_nop 1
	v_mov_b64_e32 v[140:141], v[204:205]
	v_mov_b64_e32 v[142:143], v[206:207]
	v_pk_fma_f32 v[140:141], v[156:157], v[136:137], v[140:141]
	v_pk_fma_f32 v[142:143], v[154:155], v[138:139], v[142:143]
	v_mul_f32_e32 v181, v141, v141
	global_store_dwordx4 v[166:167], v[140:143], off offset:64
	v_fmac_f32_e32 v181, v140, v140
	v_mul_f32_e32 v182, v143, v143
	v_pk_mul_f32 v[140:141], v[48:49], v[140:141]
	v_fmac_f32_e32 v182, v142, v142
	v_pk_mul_f32 v[142:143], v[50:51], v[142:143]
	v_cvt_pk_bf16_f32 v140, v140, v141
	v_add_f32_e32 v181, v181, v182
	v_cvt_pk_bf16_f32 v141, v142, v143
	global_store_dwordx2 v[170:171], v[140:141], off offset:32
	s_nop 1
	v_mov_b64_e32 v[140:141], v[208:209]
	v_mov_b64_e32 v[142:143], v[210:211]
	v_add_f32_e32 v180, v180, v181
	v_pk_fma_f32 v[140:141], v[156:157], v[132:133], v[140:141]
	v_pk_fma_f32 v[142:143], v[154:155], v[134:135], v[142:143]
	v_mul_f32_e32 v181, v141, v141
	global_store_dwordx4 v[166:167], v[140:143], off offset:512
	v_fmac_f32_e32 v181, v140, v140
	v_mul_f32_e32 v182, v143, v143
	v_pk_mul_f32 v[140:141], v[52:53], v[140:141]
	v_fmac_f32_e32 v182, v142, v142
	v_pk_mul_f32 v[142:143], v[54:55], v[142:143]
	v_cvt_pk_bf16_f32 v140, v140, v141
	v_add_f32_e32 v181, v181, v182
	v_cvt_pk_bf16_f32 v141, v142, v143
	global_store_dwordx2 v[170:171], v[140:141], off offset:256
	s_nop 1
	v_mov_b64_e32 v[140:141], v[212:213]
	v_mov_b64_e32 v[142:143], v[214:215]
	v_add_f32_e32 v190, v180, v181
	v_pk_fma_f32 v[142:143], v[154:155], v[126:127], v[142:143]
	v_pk_fma_f32 v[140:141], v[156:157], v[124:125], v[140:141]
	global_store_dwordx4 v[166:167], v[140:143], off offset:576
	v_pk_mul_f32 v[182:183], v[44:45], v[140:141]
	v_pk_mul_f32 v[180:181], v[46:47], v[142:143]
	v_mul_f32_e32 v141, v141, v141
	v_fmac_f32_e32 v141, v140, v140
	v_mul_f32_e32 v140, v143, v143
	v_fmac_f32_e32 v140, v142, v142
	v_and_b32_e32 v142, 64, v176
	v_add_f32_e32 v140, v141, v140
	v_xor_b32_e32 v141, 16, v176
	v_add_u32_e32 v142, 64, v142
	v_cmp_lt_i32_e32 vcc, v141, v142
	v_add_f32_e32 v140, v190, v140
	v_cvt_pk_bf16_f32 v182, v182, v183
	v_cvt_pk_bf16_f32 v183, v180, v181
	global_store_dwordx2 v[170:171], v[182:183], off offset:288
	v_cndmask_b32_e32 v141, v176, v141, vcc
	v_lshlrev_b32_e32 v141, 2, v141
	ds_bpermute_b32 v141, v141, v140
	s_waitcnt lgkmcnt(0)
	v_add_f32_e32 v140, v140, v141
	v_xor_b32_e32 v141, 32, v176
	v_cmp_lt_i32_e32 vcc, v141, v142
	s_nop 1
	v_cndmask_b32_e32 v141, v176, v141, vcc
	v_lshlrev_b32_e32 v141, 2, v141
	ds_bpermute_b32 v141, v141, v140
	s_and_saveexec_b64 s[0:1], s[38:39]
	s_cbranch_execz .LBB0_505
	v_lshl_add_u64 v[142:143], v[162:163], 2, s[20:21]
	s_waitcnt lgkmcnt(0)
	v_add_f32_e32 v140, v140, v141
	global_atomic_add_f32 v[142:143], v140, off

; __device__ __forceinline__ unsigned cvt_pk_bf16(float lo, float hi) { unsigned r; asm volatile("v_cvt_pk_bf16_f32 %0, %1, %2" : "=v"(r) : "v"(lo), "v"(hi)); return r; }
;     __device__ __forceinline__ void operator()(const f32x4 (&acc)[2][2][4][2], const Unit& u, int wr, int wc, int fr, int fq) const {
;     ...
;             for (int m = 0; m < 4; ++m) { const int row = u.pm * BM + ai * HALF + wr * 64 + m * 16 + fr; const size_t off = (size_t)row * ldc + col0;
;                 float ssum = 0.f;
; #pragma unroll
;                 for (int bj = 0; bj < 2; ++bj)
; #pragma unroll
;                     for (int n = 0; n < 2; ++n) { f32x4* p = (f32x4*)(X + off + bj * HALF + n * 16); const f32x4 v = *(const f32x4*)(Xin + off + bj * HALF + n * 16) + acc[ai][bj][m][n] * scale; *p = v;
;                         if (gnext) { ssum += (v.x * v.x + v.y * v.y) + (v.z * v.z + v.w * v.w); const f32x4 o = v * gv[bj][n];
;                             u32x2 w; w.x = cvt_pk_bf16(o.x, o.y); w.y = cvt_pk_bf16(o.z, o.w); *(u32x2*)(XB + off + bj * HALF + n * 16) = w; } }
;                 if (gnext) { ssum += __shfl_xor(ssum, 16); ssum += __shfl_xor(ssum, 32); if (fq == 0) unsafeAtomicAdd(SS + row, ssum); } }
.LBB0_506:
	s_waitcnt lgkmcnt(0)
	s_nop 1
	v_mov_b64_e32 v[140:141], v[204:205]
	v_mov_b64_e32 v[142:143], v[206:207]
	v_mov_b32_e32 v155, v154
	v_pk_fma_f32 v[138:139], v[154:155], v[138:139], v[142:143]
	v_pk_fma_f32 v[136:137], v[156:157], v[136:137], v[140:141]
	global_store_dwordx4 v[166:167], v[136:139], off offset:64
	s_nop 1
	v_mov_b64_e32 v[136:137], v[208:209]
	v_mov_b64_e32 v[138:139], v[210:211]
	v_pk_fma_f32 v[134:135], v[154:155], v[134:135], v[138:139]
	v_pk_fma_f32 v[132:133], v[156:157], v[132:133], v[136:137]
	global_store_dwordx4 v[166:167], v[132:135], off offset:512
	s_nop 1
	v_mov_b64_e32 v[132:133], v[212:213]
	v_mov_b64_e32 v[134:135], v[214:215]
	v_pk_fma_f32 v[126:127], v[154:155], v[126:127], v[134:135]
	v_pk_fma_f32 v[124:125], v[156:157], v[124:125], v[132:133]
	global_store_dwordx4 v[166:167], v[124:127], off offset:576
.LBB0_507:
	s_nop 1
	v_or_b32_e32 v124, 16, v162
	v_ashrrev_i32_e32 v125, 31, v124
	v_lshlrev_b64 v[124:125], 11, v[124:125]
	v_lshl_add_u64 v[136:137], v[124:125], 0, v[164:165]
	v_lshlrev_b64 v[132:133], 2, v[136:137]
	v_lshl_add_u64 v[134:135], s[6:7], 0, v[132:133]
	s_nop 1
	v_mov_b64_e32 v[124:125], v[216:217]
	v_mov_b64_e32 v[126:127], v[218:219]
	v_mov_b32_e32 v155, v154
	v_lshl_add_u64 v[132:133], s[16:17], 0, v[132:133]
	s_and_b64 vcc, exec, s[42:43]
	v_pk_fma_f32 v[126:127], v[154:155], v[130:131], v[126:127]
	v_pk_fma_f32 v[124:125], v[156:157], v[128:129], v[124:125]
	global_store_dwordx4 v[132:133], v[124:127], off
	s_cbranch_vccnz .LBB0_546
	v_mul_f32_e32 v128, v125, v125
	v_mul_f32_e32 v129, v127, v127
	v_fmac_f32_e32 v128, v124, v124
	v_fmac_f32_e32 v129, v126, v126
	v_add_f32_e32 v130, v128, v129
	v_pk_mul_f32 v[124:125], v[56:57], v[124:125]
	v_lshl_add_u64 v[128:129], v[136:137], 1, s[10:11]
	v_pk_mul_f32 v[126:127], v[58:59], v[126:127]
	v_cvt_pk_bf16_f32 v124, v124, v125
	s_nop 0
	v_cvt_pk_bf16_f32 v125, v126, v127
	global_store_dwordx2 v[128:129], v[124:125], off
	s_nop 1
	v_mov_b64_e32 v[124:125], v[220:221]
	v_mov_b64_e32 v[126:127], v[222:223]
	v_pk_fma_f32 v[124:125], v[156:157], v[120:121], v[124:125]
	v_pk_fma_f32 v[126:127], v[154:155], v[122:123], v[126:127]
	v_mul_f32_e32 v131, v125, v125
	global_store_dwordx4 v[132:133], v[124:127], off offset:64
	v_fmac_f32_e32 v131, v124, v124
	v_mul_f32_e32 v136, v127, v127
	v_pk_mul_f32 v[124:125], v[48:49], v[124:125]
	v_fmac_f32_e32 v136, v126, v126
	v_pk_mul_f32 v[126:127], v[50:51], v[126:127]
	v_cvt_pk_bf16_f32 v124, v124, v125
	v_add_f32_e32 v131, v131, v136
	v_cvt_pk_bf16_f32 v125, v126, v127
	global_store_dwordx2 v[128:129], v[124:125], off offset:32
	s_nop 1
	v_mov_b64_e32 v[124:125], v[224:225]
	v_mov_b64_e32 v[126:127], v[226:227]
	v_add_f32_e32 v130, v130, v131
	v_pk_fma_f32 v[124:125], v[156:157], v[116:117], v[124:125]
	v_pk_fma_f32 v[126:127], v[154:155], v[118:119], v[126:127]
	v_mul_f32_e32 v131, v125, v125
	global_store_dwordx4 v[132:133], v[124:127], off offset:512
	v_fmac_f32_e32 v131, v124, v124
	v_mul_f32_e32 v136, v127, v127
	v_pk_mul_f32 v[124:125], v[52:53], v[124:125]
	v_fmac_f32_e32 v136, v126, v126
	v_pk_mul_f32 v[126:127], v[54:55], v[126:127]
	v_cvt_pk_bf16_f32 v124, v124, v125
	v_add_f32_e32 v131, v131, v136
	v_cvt_pk_bf16_f32 v125, v126, v127
	global_store_dwordx2 v[128:129], v[124:125], off offset:256
	s_nop 1
	v_mov_b64_e32 v[124:125], v[228:229]
	v_mov_b64_e32 v[126:127], v[230:231]
	v_add_f32_e32 v138, v130, v131
	v_pk_fma_f32 v[126:127], v[154:155], v[110:111], v[126:127]
	v_pk_fma_f32 v[124:125], v[156:157], v[108:109], v[124:125]
	global_store_dwordx4 v[132:133], v[124:127], off offset:576
	v_pk_mul_f32 v[136:137], v[44:45], v[124:125]
	v_pk_mul_f32 v[130:131], v[46:47], v[126:127]
	v_mul_f32_e32 v125, v125, v125
	v_fmac_f32_e32 v125, v124, v124
	v_mul_f32_e32 v124, v127, v127
	v_fmac_f32_e32 v124, v126, v126
	v_and_b32_e32 v126, 64, v176
	v_add_f32_e32 v124, v125, v124
	v_xor_b32_e32 v125, 16, v176
	v_add_u32_e32 v126, 64, v126
	v_cmp_lt_i32_e32 vcc, v125, v126
	v_add_f32_e32 v124, v138, v124
	v_cvt_pk_bf16_f32 v136, v136, v137
	v_cvt_pk_bf16_f32 v137, v130, v131
	global_store_dwordx2 v[128:129], v[136:137], off offset:288
	v_cndmask_b32_e32 v125, v176, v125, vcc
	v_lshlrev_b32_e32 v125, 2, v125
	ds_bpermute_b32 v125, v125, v124
	s_waitcnt lgkmcnt(0)
	v_add_f32_e32 v124, v124, v125
	v_xor_b32_e32 v125, 32, v176
	v_cmp_lt_i32_e32 vcc, v125, v126
	s_nop 1
	v_cndmask_b32_e32 v125, v176, v125, vcc
	v_lshlrev_b32_e32 v125, 2, v125
	ds_bpermute_b32 v125, v125, v124
	s_and_saveexec_b64 s[0:1], s[38:39]
	s_cbranch_execz .LBB0_510
	v_lshl_add_u64 v[126:127], v[162:163], 2, s[20:21]
	s_waitcnt lgkmcnt(0)
	v_add_f32_e32 v124, v124, v125
	global_atomic_add_f32 v[126:127], v124, off offset:64

; __device__ __forceinline__ unsigned cvt_pk_bf16(float lo, float hi) { unsigned r; asm volatile("v_cvt_pk_bf16_f32 %0, %1, %2" : "=v"(r) : "v"(lo), "v"(hi)); return r; }
;     __device__ __forceinline__ void operator()(const f32x4 (&acc)[2][2][4][2], const Unit& u, int wr, int wc, int fr, int fq) const {
;     ...
;             for (int m = 0; m < 4; ++m) { const int row = u.pm * BM + ai * HALF + wr * 64 + m * 16 + fr; const size_t off = (size_t)row * ldc + col0;
;                 float ssum = 0.f;
; #pragma unroll
;                 for (int bj = 0; bj < 2; ++bj)
; #pragma unroll
;                     for (int n = 0; n < 2; ++n) { f32x4* p = (f32x4*)(X + off + bj * HALF + n * 16); const f32x4 v = *(const f32x4*)(Xin + off + bj * HALF + n * 16) + acc[ai][bj][m][n] * scale; *p = v;
;                         if (gnext) { ssum += (v.x * v.x + v.y * v.y) + (v.z * v.z + v.w * v.w); const f32x4 o = v * gv[bj][n];
;                             u32x2 w; w.x = cvt_pk_bf16(o.x, o.y); w.y = cvt_pk_bf16(o.z, o.w); *(u32x2*)(XB + off + bj * HALF + n * 16) = w; } }
;                 if (gnext) { ssum += __shfl_xor(ssum, 16); ssum += __shfl_xor(ssum, 32); if (fq == 0) unsafeAtomicAdd(SS + row, ssum); } }
.LBB0_511:
	s_waitcnt lgkmcnt(0)
	s_nop 1
	v_mov_b64_e32 v[124:125], v[220:221]
	v_mov_b64_e32 v[126:127], v[222:223]
	v_mov_b32_e32 v155, v154
	v_pk_fma_f32 v[122:123], v[154:155], v[122:123], v[126:127]
	v_pk_fma_f32 v[120:121], v[156:157], v[120:121], v[124:125]
	global_store_dwordx4 v[132:133], v[120:123], off offset:64
	s_nop 1
	v_mov_b64_e32 v[120:121], v[224:225]
	v_mov_b64_e32 v[122:123], v[226:227]
	v_pk_fma_f32 v[118:119], v[154:155], v[118:119], v[122:123]
	v_pk_fma_f32 v[116:117], v[156:157], v[116:117], v[120:121]
	global_store_dwordx4 v[132:133], v[116:119], off offset:512
	s_nop 1
	v_mov_b64_e32 v[116:117], v[228:229]
	v_mov_b64_e32 v[118:119], v[230:231]
	v_pk_fma_f32 v[110:111], v[154:155], v[110:111], v[118:119]
	v_pk_fma_f32 v[108:109], v[156:157], v[108:109], v[116:117]
	global_store_dwordx4 v[132:133], v[108:111], off offset:576
.LBB0_512:
	s_nop 1
	v_or_b32_e32 v108, 32, v162
	v_ashrrev_i32_e32 v109, 31, v108
	v_lshlrev_b64 v[108:109], 11, v[108:109]
	v_lshl_add_u64 v[120:121], v[108:109], 0, v[164:165]
	v_lshlrev_b64 v[116:117], 2, v[120:121]
	v_lshl_add_u64 v[118:119], s[6:7], 0, v[116:117]
	s_nop 1
	v_mov_b64_e32 v[108:109], v[232:233]
	v_mov_b64_e32 v[110:111], v[234:235]
	v_mov_b32_e32 v155, v154
	v_lshl_add_u64 v[116:117], s[16:17], 0, v[116:117]
	s_and_b64 vcc, exec, s[42:43]
	v_pk_fma_f32 v[110:111], v[154:155], v[114:115], v[110:111]
	v_pk_fma_f32 v[108:109], v[156:157], v[112:113], v[108:109]
	global_store_dwordx4 v[116:117], v[108:111], off
	s_cbranch_vccnz .LBB0_547
	v_mul_f32_e32 v112, v109, v109
	v_mul_f32_e32 v113, v111, v111
	v_fmac_f32_e32 v112, v108, v108
	v_fmac_f32_e32 v113, v110, v110
	v_add_f32_e32 v114, v112, v113
	v_pk_mul_f32 v[108:109], v[56:57], v[108:109]
	v_lshl_add_u64 v[112:113], v[120:121], 1, s[10:11]
	v_pk_mul_f32 v[110:111], v[58:59], v[110:111]
	v_cvt_pk_bf16_f32 v108, v108, v109
	s_nop 0
	v_cvt_pk_bf16_f32 v109, v110, v111
	global_store_dwordx2 v[112:113], v[108:109], off
	s_nop 1
	v_mov_b64_e32 v[108:109], v[236:237]
	v_mov_b64_e32 v[110:111], v[238:239]
	v_pk_fma_f32 v[108:109], v[156:157], v[104:105], v[108:109]
	v_pk_fma_f32 v[110:111], v[154:155], v[106:107], v[110:111]
	v_mul_f32_e32 v115, v109, v109
	global_store_dwordx4 v[116:117], v[108:111], off offset:64
	v_fmac_f32_e32 v115, v108, v108
	v_mul_f32_e32 v120, v111, v111
	v_pk_mul_f32 v[108:109], v[48:49], v[108:109]
	v_fmac_f32_e32 v120, v110, v110
	v_pk_mul_f32 v[110:111], v[50:51], v[110:111]
	v_cvt_pk_bf16_f32 v108, v108, v109
	v_add_f32_e32 v115, v115, v120
	v_cvt_pk_bf16_f32 v109, v110, v111
	global_store_dwordx2 v[112:113], v[108:109], off offset:32
	s_nop 1
	v_mov_b64_e32 v[108:109], v[240:241]
	v_mov_b64_e32 v[110:111], v[242:243]
	v_add_f32_e32 v114, v114, v115
	v_pk_fma_f32 v[108:109], v[156:157], v[100:101], v[108:109]
	v_pk_fma_f32 v[110:111], v[154:155], v[102:103], v[110:111]
	v_mul_f32_e32 v115, v109, v109
	global_store_dwordx4 v[116:117], v[108:111], off offset:512
	v_fmac_f32_e32 v115, v108, v108
	v_mul_f32_e32 v120, v111, v111
	v_pk_mul_f32 v[108:109], v[52:53], v[108:109]
	v_fmac_f32_e32 v120, v110, v110
	v_pk_mul_f32 v[110:111], v[54:55], v[110:111]
	v_cvt_pk_bf16_f32 v108, v108, v109
	v_add_f32_e32 v115, v115, v120
	v_cvt_pk_bf16_f32 v109, v110, v111
	global_store_dwordx2 v[112:113], v[108:109], off offset:256
	s_nop 1
	v_mov_b64_e32 v[108:109], v[244:245]
	v_mov_b64_e32 v[110:111], v[246:247]
	v_add_f32_e32 v122, v114, v115
	v_pk_fma_f32 v[110:111], v[154:155], v[94:95], v[110:111]
	v_pk_fma_f32 v[108:109], v[156:157], v[92:93], v[108:109]
	global_store_dwordx4 v[116:117], v[108:111], off offset:576
	v_pk_mul_f32 v[120:121], v[44:45], v[108:109]
	v_pk_mul_f32 v[114:115], v[46:47], v[110:111]
	v_mul_f32_e32 v109, v109, v109
	v_fmac_f32_e32 v109, v108, v108
	v_mul_f32_e32 v108, v111, v111
	v_fmac_f32_e32 v108, v110, v110
	v_and_b32_e32 v110, 64, v176
	v_add_f32_e32 v108, v109, v108
	v_xor_b32_e32 v109, 16, v176
	v_add_u32_e32 v110, 64, v110
	v_cmp_lt_i32_e32 vcc, v109, v110
	v_add_f32_e32 v108, v122, v108
	v_cvt_pk_bf16_f32 v120, v120, v121
	v_cvt_pk_bf16_f32 v121, v114, v115
	global_store_dwordx2 v[112:113], v[120:121], off offset:288
	v_cndmask_b32_e32 v109, v176, v109, vcc
	v_lshlrev_b32_e32 v109, 2, v109
	ds_bpermute_b32 v109, v109, v108
	s_waitcnt lgkmcnt(0)
	v_add_f32_e32 v108, v108, v109
	v_xor_b32_e32 v109, 32, v176
	v_cmp_lt_i32_e32 vcc, v109, v110
	s_nop 1
	v_cndmask_b32_e32 v109, v176, v109, vcc
	v_lshlrev_b32_e32 v109, 2, v109
	ds_bpermute_b32 v109, v109, v108
	s_and_saveexec_b64 s[0:1], s[38:39]
	s_cbranch_execz .LBB0_515
	v_lshl_add_u64 v[110:111], v[162:163], 2, s[20:21]
	s_waitcnt lgkmcnt(0)
	v_add_f32_e32 v108, v108, v109
	global_atomic_add_f32 v[110:111], v108, off offset:128

; __device__ __forceinline__ unsigned cvt_pk_bf16(float lo, float hi) { unsigned r; asm volatile("v_cvt_pk_bf16_f32 %0, %1, %2" : "=v"(r) : "v"(lo), "v"(hi)); return r; }
;     __device__ __forceinline__ void operator()(const f32x4 (&acc)[2][2][4][2], const Unit& u, int wr, int wc, int fr, int fq) const {
;     ...
;             for (int m = 0; m < 4; ++m) { const int row = u.pm * BM + ai * HALF + wr * 64 + m * 16 + fr; const size_t off = (size_t)row * ldc + col0;
;                 float ssum = 0.f;
; #pragma unroll
;                 for (int bj = 0; bj < 2; ++bj)
; #pragma unroll
;                     for (int n = 0; n < 2; ++n) { f32x4* p = (f32x4*)(X + off + bj * HALF + n * 16); const f32x4 v = *(const f32x4*)(Xin + off + bj * HALF + n * 16) + acc[ai][bj][m][n] * scale; *p = v;
;                         if (gnext) { ssum += (v.x * v.x + v.y * v.y) + (v.z * v.z + v.w * v.w); const f32x4 o = v * gv[bj][n];
;                             u32x2 w; w.x = cvt_pk_bf16(o.x, o.y); w.y = cvt_pk_bf16(o.z, o.w); *(u32x2*)(XB + off + bj * HALF + n * 16) = w; } }
;                 if (gnext) { ssum += __shfl_xor(ssum, 16); ssum += __shfl_xor(ssum, 32); if (fq == 0) unsafeAtomicAdd(SS + row, ssum); } }
.LBB0_516:
	s_waitcnt lgkmcnt(0)
	s_nop 1
	v_mov_b64_e32 v[108:109], v[236:237]
	v_mov_b64_e32 v[110:111], v[238:239]
	v_mov_b32_e32 v155, v154
	v_pk_fma_f32 v[106:107], v[154:155], v[106:107], v[110:111]
	v_pk_fma_f32 v[104:105], v[156:157], v[104:105], v[108:109]
	global_store_dwordx4 v[116:117], v[104:107], off offset:64
	s_nop 1
	v_mov_b64_e32 v[104:105], v[240:241]
	v_mov_b64_e32 v[106:107], v[242:243]
	v_pk_fma_f32 v[102:103], v[154:155], v[102:103], v[106:107]
	v_pk_fma_f32 v[100:101], v[156:157], v[100:101], v[104:105]
	global_store_dwordx4 v[116:117], v[100:103], off offset:512
	s_nop 1
	v_mov_b64_e32 v[100:101], v[244:245]
	v_mov_b64_e32 v[102:103], v[246:247]
	v_pk_fma_f32 v[94:95], v[154:155], v[94:95], v[102:103]
	v_pk_fma_f32 v[92:93], v[156:157], v[92:93], v[100:101]
	global_store_dwordx4 v[116:117], v[92:95], off offset:576
.LBB0_517:
	s_nop 1
	v_add_u32_e32 v194, 0x30, v162
	v_ashrrev_i32_e32 v195, 31, v194
	v_lshlrev_b64 v[194:195], 11, v[194:195]
	v_lshl_add_u64 v[194:195], v[194:195], 0, v[164:165]
	v_lshlrev_b64 v[194:195], 2, v[194:195]
	v_lshl_add_u64 v[194:195], s[6:7], 0, v[194:195]
	global_load_dwordx4 v[200:203], v[194:195], off
	global_load_dwordx4 v[204:207], v[194:195], off offset:64
	global_load_dwordx4 v[208:211], v[194:195], off offset:512
	global_load_dwordx4 v[212:215], v[194:195], off offset:576
	v_add_u32_e32 v196, 0x80, v162
	v_ashrrev_i32_e32 v197, 31, v196
	v_lshlrev_b64 v[196:197], 11, v[196:197]
	v_lshl_add_u64 v[196:197], v[196:197], 0, v[164:165]
	v_lshlrev_b64 v[196:197], 2, v[196:197]
	v_lshl_add_u64 v[196:197], s[6:7], 0, v[196:197]
	global_load_dwordx4 v[216:219], v[196:197], off
	global_load_dwordx4 v[220:223], v[196:197], off offset:64
	global_load_dwordx4 v[224:227], v[196:197], off offset:512
	global_load_dwordx4 v[228:231], v[196:197], off offset:576
	v_add_u32_e32 v198, 0x90, v162
	v_ashrrev_i32_e32 v199, 31, v198
	v_lshlrev_b64 v[198:199], 11, v[198:199]
	v_lshl_add_u64 v[198:199], v[198:199], 0, v[164:165]
	v_lshlrev_b64 v[198:199], 2, v[198:199]
	v_lshl_add_u64 v[198:199], s[6:7], 0, v[198:199]
	global_load_dwordx4 v[232:235], v[198:199], off
	global_load_dwordx4 v[236:239], v[198:199], off offset:64
	global_load_dwordx4 v[240:243], v[198:199], off offset:512
	global_load_dwordx4 v[244:247], v[198:199], off offset:576
	s_waitcnt vmcnt(0)
	v_or_b32_e32 v92, 48, v162
	v_ashrrev_i32_e32 v93, 31, v92
	v_lshlrev_b64 v[92:93], 11, v[92:93]
	v_lshl_add_u64 v[104:105], v[92:93], 0, v[164:165]
	v_lshlrev_b64 v[100:101], 2, v[104:105]
	v_lshl_add_u64 v[102:103], s[6:7], 0, v[100:101]
	s_nop 1
	v_mov_b64_e32 v[92:93], v[200:201]
	v_mov_b64_e32 v[94:95], v[202:203]
	v_mov_b32_e32 v155, v154
	v_lshl_add_u64 v[100:101], s[16:17], 0, v[100:101]
	s_and_b64 vcc, exec, s[42:43]
	v_pk_fma_f32 v[94:95], v[154:155], v[98:99], v[94:95]
	v_pk_fma_f32 v[92:93], v[156:157], v[96:97], v[92:93]
	global_store_dwordx4 v[100:101], v[92:95], off
	s_cbranch_vccnz .LBB0_548
	v_mul_f32_e32 v96, v93, v93
	v_mul_f32_e32 v97, v95, v95
	v_fmac_f32_e32 v96, v92, v92
	v_fmac_f32_e32 v97, v94, v94
	v_add_f32_e32 v98, v96, v97
	v_pk_mul_f32 v[92:93], v[56:57], v[92:93]
	v_lshl_add_u64 v[96:97], v[104:105], 1, s[10:11]
	v_pk_mul_f32 v[94:95], v[58:59], v[94:95]
	v_cvt_pk_bf16_f32 v92, v92, v93
	s_nop 0
	v_cvt_pk_bf16_f32 v93, v94, v95
	global_store_dwordx2 v[96:97], v[92:93], off
	s_nop 1
	v_mov_b64_e32 v[92:93], v[204:205]
	v_mov_b64_e32 v[94:95], v[206:207]
	v_pk_fma_f32 v[92:93], v[156:157], v[88:89], v[92:93]
	v_pk_fma_f32 v[94:95], v[154:155], v[90:91], v[94:95]
	v_mul_f32_e32 v99, v93, v93
	global_store_dwordx4 v[100:101], v[92:95], off offset:64
	v_fmac_f32_e32 v99, v92, v92
	v_mul_f32_e32 v104, v95, v95
	v_pk_mul_f32 v[92:93], v[48:49], v[92:93]
	v_fmac_f32_e32 v104, v94, v94
	v_pk_mul_f32 v[94:95], v[50:51], v[94:95]
	v_cvt_pk_bf16_f32 v92, v92, v93
	v_add_f32_e32 v99, v99, v104
	v_cvt_pk_bf16_f32 v93, v94, v95
	global_store_dwordx2 v[96:97], v[92:93], off offset:32
	s_nop 1
	v_mov_b64_e32 v[92:93], v[208:209]
	v_mov_b64_e32 v[94:95], v[210:211]
	v_add_f32_e32 v98, v98, v99
	v_pk_fma_f32 v[92:93], v[156:157], v[84:85], v[92:93]
	v_pk_fma_f32 v[94:95], v[154:155], v[86:87], v[94:95]
	v_mul_f32_e32 v99, v93, v93
	global_store_dwordx4 v[100:101], v[92:95], off offset:512
	v_fmac_f32_e32 v99, v92, v92
	v_mul_f32_e32 v104, v95, v95
	v_pk_mul_f32 v[92:93], v[52:53], v[92:93]
	v_fmac_f32_e32 v104, v94, v94
	v_pk_mul_f32 v[94:95], v[54:55], v[94:95]
	v_cvt_pk_bf16_f32 v92, v92, v93
	v_add_f32_e32 v99, v99, v104
	v_cvt_pk_bf16_f32 v93, v94, v95
	global_store_dwordx2 v[96:97], v[92:93], off offset:256
	s_nop 1
	v_mov_b64_e32 v[92:93], v[212:213]
	v_mov_b64_e32 v[94:95], v[214:215]
	v_add_f32_e32 v106, v98, v99
	v_pk_fma_f32 v[94:95], v[154:155], v[82:83], v[94:95]
	v_pk_fma_f32 v[92:93], v[156:157], v[80:81], v[92:93]
	global_store_dwordx4 v[100:101], v[92:95], off offset:576
	v_pk_mul_f32 v[104:105], v[44:45], v[92:93]
	v_pk_mul_f32 v[98:99], v[46:47], v[94:95]
	v_mul_f32_e32 v93, v93, v93
	v_fmac_f32_e32 v93, v92, v92
	v_mul_f32_e32 v92, v95, v95
	v_fmac_f32_e32 v92, v94, v94
	v_and_b32_e32 v94, 64, v176
	v_add_f32_e32 v92, v93, v92
	v_xor_b32_e32 v93, 16, v176
	v_add_u32_e32 v94, 64, v94
	v_cmp_lt_i32_e32 vcc, v93, v94
	v_add_f32_e32 v92, v106, v92
	v_cvt_pk_bf16_f32 v104, v104, v105
	v_cvt_pk_bf16_f32 v105, v98, v99
	global_store_dwordx2 v[96:97], v[104:105], off offset:288
	v_cndmask_b32_e32 v93, v176, v93, vcc
	v_lshlrev_b32_e32 v93, 2, v93
	ds_bpermute_b32 v93, v93, v92
	s_waitcnt lgkmcnt(0)
	v_add_f32_e32 v92, v92, v93
	v_xor_b32_e32 v93, 32, v176
	v_cmp_lt_i32_e32 vcc, v93, v94
	s_nop 1
	v_cndmask_b32_e32 v93, v176, v93, vcc
	v_lshlrev_b32_e32 v93, 2, v93
	ds_bpermute_b32 v93, v93, v92
	s_and_saveexec_b64 s[0:1], s[38:39]
	s_cbranch_execz .LBB0_520
	v_lshl_add_u64 v[94:95], v[162:163], 2, s[20:21]
	s_waitcnt lgkmcnt(0)
	v_add_f32_e32 v92, v92, v93
	global_atomic_add_f32 v[94:95], v92, off offset:192

; __device__ __forceinline__ unsigned cvt_pk_bf16(float lo, float hi) { unsigned r; asm volatile("v_cvt_pk_bf16_f32 %0, %1, %2" : "=v"(r) : "v"(lo), "v"(hi)); return r; }
;     __device__ __forceinline__ void operator()(const f32x4 (&acc)[2][2][4][2], const Unit& u, int wr, int wc, int fr, int fq) const {
;     ...
;             for (int m = 0; m < 4; ++m) { const int row = u.pm * BM + ai * HALF + wr * 64 + m * 16 + fr; const size_t off = (size_t)row * ldc + col0;
;                 float ssum = 0.f;
; #pragma unroll
;                 for (int bj = 0; bj < 2; ++bj)
; #pragma unroll
;                     for (int n = 0; n < 2; ++n) { f32x4* p = (f32x4*)(X + off + bj * HALF + n * 16); const f32x4 v = *(const f32x4*)(Xin + off + bj * HALF + n * 16) + acc[ai][bj][m][n] * scale; *p = v;
;                         if (gnext) { ssum += (v.x * v.x + v.y * v.y) + (v.z * v.z + v.w * v.w); const f32x4 o = v * gv[bj][n];
;                             u32x2 w; w.x = cvt_pk_bf16(o.x, o.y); w.y = cvt_pk_bf16(o.z, o.w); *(u32x2*)(XB + off + bj * HALF + n * 16) = w; } }
;                 if (gnext) { ssum += __shfl_xor(ssum, 16); ssum += __shfl_xor(ssum, 32); if (fq == 0) unsafeAtomicAdd(SS + row, ssum); } }
.LBB0_521:
	s_waitcnt lgkmcnt(0)
	s_nop 1
	v_mov_b64_e32 v[92:93], v[204:205]
	v_mov_b64_e32 v[94:95], v[206:207]
	v_mov_b32_e32 v155, v154
	v_pk_fma_f32 v[90:91], v[154:155], v[90:91], v[94:95]
	v_pk_fma_f32 v[88:89], v[156:157], v[88:89], v[92:93]
	global_store_dwordx4 v[100:101], v[88:91], off offset:64
	s_nop 1
	v_mov_b64_e32 v[88:89], v[208:209]
	v_mov_b64_e32 v[90:91], v[210:211]
	v_pk_fma_f32 v[86:87], v[154:155], v[86:87], v[90:91]
	v_pk_fma_f32 v[84:85], v[156:157], v[84:85], v[88:89]
	global_store_dwordx4 v[100:101], v[84:87], off offset:512
	s_nop 1
	v_mov_b64_e32 v[84:85], v[212:213]
	v_mov_b64_e32 v[86:87], v[214:215]
	v_pk_fma_f32 v[82:83], v[154:155], v[82:83], v[86:87]
	v_pk_fma_f32 v[80:81], v[156:157], v[80:81], v[84:85]
	global_store_dwordx4 v[100:101], v[80:83], off offset:576
.LBB0_522:
	s_nop 1
	v_add_u32_e32 v80, 0x80, v162
	v_ashrrev_i32_e32 v81, 31, v80
	v_lshlrev_b64 v[80:81], 11, v[80:81]
	v_lshl_add_u64 v[84:85], v[80:81], 0, v[164:165]
	v_lshlrev_b64 v[80:81], 2, v[84:85]
	v_lshl_add_u64 v[82:83], s[6:7], 0, v[80:81]
	s_nop 1
	v_mov_b64_e32 v[86:87], v[216:217]
	v_mov_b64_e32 v[88:89], v[218:219]
	v_mov_b32_e32 v155, v154
	v_lshl_add_u64 v[80:81], s[16:17], 0, v[80:81]
	s_and_b64 vcc, exec, s[42:43]
	v_pk_fma_f32 v[78:79], v[154:155], v[78:79], v[88:89]
	v_pk_fma_f32 v[76:77], v[156:157], v[76:77], v[86:87]
	global_store_dwordx4 v[80:81], v[76:79], off
	s_cbranch_vccnz .LBB0_549
	v_mul_f32_e32 v86, v77, v77
	v_fmac_f32_e32 v86, v76, v76
	v_mul_f32_e32 v87, v79, v79
	v_pk_mul_f32 v[76:77], v[56:57], v[76:77]
	v_lshl_add_u64 v[84:85], v[84:85], 1, s[10:11]
	v_fmac_f32_e32 v87, v78, v78
	v_pk_mul_f32 v[78:79], v[58:59], v[78:79]
	v_cvt_pk_bf16_f32 v76, v76, v77
	v_add_f32_e32 v86, v86, v87
	v_cvt_pk_bf16_f32 v77, v78, v79
	global_store_dwordx2 v[84:85], v[76:77], off
	s_nop 1
	v_mov_b64_e32 v[76:77], v[220:221]
	v_mov_b64_e32 v[78:79], v[222:223]
	v_pk_fma_f32 v[76:77], v[156:157], v[72:73], v[76:77]
	v_pk_fma_f32 v[78:79], v[154:155], v[74:75], v[78:79]
	v_mul_f32_e32 v87, v77, v77
	global_store_dwordx4 v[80:81], v[76:79], off offset:64
	v_fmac_f32_e32 v87, v76, v76
	v_mul_f32_e32 v88, v79, v79
	v_pk_mul_f32 v[76:77], v[48:49], v[76:77]
	v_fmac_f32_e32 v88, v78, v78
	v_pk_mul_f32 v[78:79], v[50:51], v[78:79]
	v_cvt_pk_bf16_f32 v76, v76, v77
	v_add_f32_e32 v87, v87, v88
	v_cvt_pk_bf16_f32 v77, v78, v79
	global_store_dwordx2 v[84:85], v[76:77], off offset:32
	s_nop 1
	v_mov_b64_e32 v[76:77], v[224:225]
	v_mov_b64_e32 v[78:79], v[226:227]
	v_add_f32_e32 v86, v86, v87
	v_pk_fma_f32 v[76:77], v[156:157], v[68:69], v[76:77]
	v_pk_fma_f32 v[78:79], v[154:155], v[70:71], v[78:79]
	v_mul_f32_e32 v87, v77, v77
	global_store_dwordx4 v[80:81], v[76:79], off offset:512
	v_fmac_f32_e32 v87, v76, v76
	v_mul_f32_e32 v88, v79, v79
	v_pk_mul_f32 v[76:77], v[52:53], v[76:77]
	v_fmac_f32_e32 v88, v78, v78
	v_pk_mul_f32 v[78:79], v[54:55], v[78:79]
	v_cvt_pk_bf16_f32 v76, v76, v77
	v_add_f32_e32 v87, v87, v88
	v_cvt_pk_bf16_f32 v77, v78, v79
	global_store_dwordx2 v[84:85], v[76:77], off offset:256
	s_nop 1
	v_mov_b64_e32 v[76:77], v[228:229]
	v_mov_b64_e32 v[78:79], v[230:231]
	v_add_f32_e32 v90, v86, v87
	v_pk_fma_f32 v[78:79], v[154:155], v[62:63], v[78:79]
	v_pk_fma_f32 v[76:77], v[156:157], v[60:61], v[76:77]
	global_store_dwordx4 v[80:81], v[76:79], off offset:576
	v_pk_mul_f32 v[88:89], v[44:45], v[76:77]
	v_pk_mul_f32 v[86:87], v[46:47], v[78:79]
	v_mul_f32_e32 v77, v77, v77
	v_fmac_f32_e32 v77, v76, v76
	v_mul_f32_e32 v76, v79, v79
	v_fmac_f32_e32 v76, v78, v78
	v_and_b32_e32 v78, 64, v176
	v_add_f32_e32 v76, v77, v76
	v_xor_b32_e32 v77, 16, v176
	v_add_u32_e32 v78, 64, v78
	v_cmp_lt_i32_e32 vcc, v77, v78
	v_add_f32_e32 v76, v90, v76
	v_cvt_pk_bf16_f32 v88, v88, v89
	v_cvt_pk_bf16_f32 v89, v86, v87
	global_store_dwordx2 v[84:85], v[88:89], off offset:288
	v_cndmask_b32_e32 v77, v176, v77, vcc
	v_lshlrev_b32_e32 v77, 2, v77
	ds_bpermute_b32 v77, v77, v76
	s_waitcnt lgkmcnt(0)
	v_add_f32_e32 v76, v76, v77
	v_xor_b32_e32 v77, 32, v176
	v_cmp_lt_i32_e32 vcc, v77, v78
	s_nop 1
	v_cndmask_b32_e32 v77, v176, v77, vcc
	v_lshlrev_b32_e32 v77, 2, v77
	ds_bpermute_b32 v77, v77, v76
	s_and_saveexec_b64 s[0:1], s[38:39]
	s_cbranch_execz .LBB0_525
	v_lshl_add_u64 v[78:79], v[162:163], 2, s[20:21]
	s_waitcnt lgkmcnt(0)
	v_add_f32_e32 v76, v76, v77
	global_atomic_add_f32 v[78:79], v76, off offset:512

; __device__ __forceinline__ unsigned cvt_pk_bf16(float lo, float hi) { unsigned r; asm volatile("v_cvt_pk_bf16_f32 %0, %1, %2" : "=v"(r) : "v"(lo), "v"(hi)); return r; }
;     __device__ __forceinline__ void operator()(const f32x4 (&acc)[2][2][4][2], const Unit& u, int wr, int wc, int fr, int fq) const {
;     ...
;             for (int m = 0; m < 4; ++m) { const int row = u.pm * BM + ai * HALF + wr * 64 + m * 16 + fr; const size_t off = (size_t)row * ldc + col0;
;                 float ssum = 0.f;
; #pragma unroll
;                 for (int bj = 0; bj < 2; ++bj)
; #pragma unroll
;                     for (int n = 0; n < 2; ++n) { f32x4* p = (f32x4*)(X + off + bj * HALF + n * 16); const f32x4 v = *(const f32x4*)(Xin + off + bj * HALF + n * 16) + acc[ai][bj][m][n] * scale; *p = v;
;                         if (gnext) { ssum += (v.x * v.x + v.y * v.y) + (v.z * v.z + v.w * v.w); const f32x4 o = v * gv[bj][n];
;                             u32x2 w; w.x = cvt_pk_bf16(o.x, o.y); w.y = cvt_pk_bf16(o.z, o.w); *(u32x2*)(XB + off + bj * HALF + n * 16) = w; } }
;                 if (gnext) { ssum += __shfl_xor(ssum, 16); ssum += __shfl_xor(ssum, 32); if (fq == 0) unsafeAtomicAdd(SS + row, ssum); } }
.LBB0_526:
	s_waitcnt lgkmcnt(0)
	s_nop 1
	v_mov_b64_e32 v[76:77], v[220:221]
	v_mov_b64_e32 v[78:79], v[222:223]
	v_mov_b32_e32 v155, v154
	v_pk_fma_f32 v[74:75], v[154:155], v[74:75], v[78:79]
	v_pk_fma_f32 v[72:73], v[156:157], v[72:73], v[76:77]
	global_store_dwordx4 v[80:81], v[72:75], off offset:64
	s_nop 1
	v_mov_b64_e32 v[72:73], v[224:225]
	v_mov_b64_e32 v[74:75], v[226:227]
	v_pk_fma_f32 v[70:71], v[154:155], v[70:71], v[74:75]
	v_pk_fma_f32 v[68:69], v[156:157], v[68:69], v[72:73]
	global_store_dwordx4 v[80:81], v[68:71], off offset:512
	s_nop 1
	v_mov_b64_e32 v[68:69], v[228:229]
	v_mov_b64_e32 v[70:71], v[230:231]
	v_pk_fma_f32 v[62:63], v[154:155], v[62:63], v[70:71]
	v_pk_fma_f32 v[60:61], v[156:157], v[60:61], v[68:69]
	global_store_dwordx4 v[80:81], v[60:63], off offset:576
.LBB0_527:
	s_nop 1
	v_add_u32_e32 v60, 0x90, v162
	v_ashrrev_i32_e32 v61, 31, v60
	v_lshlrev_b64 v[60:61], 11, v[60:61]
	v_lshl_add_u64 v[72:73], v[60:61], 0, v[164:165]
	v_lshlrev_b64 v[68:69], 2, v[72:73]
	v_lshl_add_u64 v[70:71], s[6:7], 0, v[68:69]
	s_nop 1
	v_mov_b64_e32 v[60:61], v[232:233]
	v_mov_b64_e32 v[62:63], v[234:235]
	v_mov_b32_e32 v155, v154
	v_lshl_add_u64 v[68:69], s[16:17], 0, v[68:69]
	s_and_b64 vcc, exec, s[42:43]
	v_pk_fma_f32 v[62:63], v[154:155], v[66:67], v[62:63]
	v_pk_fma_f32 v[60:61], v[156:157], v[64:65], v[60:61]
	global_store_dwordx4 v[68:69], v[60:63], off
	s_cbranch_vccnz .LBB0_550
	v_mul_f32_e32 v64, v61, v61
	v_mul_f32_e32 v65, v63, v63
	v_fmac_f32_e32 v64, v60, v60
	v_fmac_f32_e32 v65, v62, v62
	v_add_f32_e32 v66, v64, v65
	v_pk_mul_f32 v[60:61], v[56:57], v[60:61]
	v_lshl_add_u64 v[64:65], v[72:73], 1, s[10:11]
	v_pk_mul_f32 v[62:63], v[58:59], v[62:63]
	v_cvt_pk_bf16_f32 v60, v60, v61
	s_nop 0
	v_cvt_pk_bf16_f32 v61, v62, v63
	global_store_dwordx2 v[64:65], v[60:61], off
	s_nop 1
	v_mov_b64_e32 v[60:61], v[236:237]
	v_mov_b64_e32 v[62:63], v[238:239]
	v_pk_fma_f32 v[60:61], v[156:157], v[40:41], v[60:61]
	v_pk_fma_f32 v[62:63], v[154:155], v[42:43], v[62:63]
	v_mul_f32_e32 v67, v61, v61
	global_store_dwordx4 v[68:69], v[60:63], off offset:64
	v_fmac_f32_e32 v67, v60, v60
	v_mul_f32_e32 v72, v63, v63
	v_pk_mul_f32 v[60:61], v[48:49], v[60:61]
	v_fmac_f32_e32 v72, v62, v62
	v_pk_mul_f32 v[62:63], v[50:51], v[62:63]
	v_cvt_pk_bf16_f32 v60, v60, v61
	v_add_f32_e32 v67, v67, v72
	v_cvt_pk_bf16_f32 v61, v62, v63
	global_store_dwordx2 v[64:65], v[60:61], off offset:32
	s_nop 1
	v_mov_b64_e32 v[60:61], v[240:241]
	v_mov_b64_e32 v[62:63], v[242:243]
	v_add_f32_e32 v66, v66, v67
	v_pk_fma_f32 v[60:61], v[156:157], v[36:37], v[60:61]
	v_pk_fma_f32 v[62:63], v[154:155], v[38:39], v[62:63]
	v_mul_f32_e32 v67, v61, v61
	global_store_dwordx4 v[68:69], v[60:63], off offset:512
	v_fmac_f32_e32 v67, v60, v60
	v_mul_f32_e32 v72, v63, v63
	v_pk_mul_f32 v[60:61], v[52:53], v[60:61]
	v_fmac_f32_e32 v72, v62, v62
	v_pk_mul_f32 v[62:63], v[54:55], v[62:63]
	v_cvt_pk_bf16_f32 v60, v60, v61
	v_add_f32_e32 v67, v67, v72
	v_cvt_pk_bf16_f32 v61, v62, v63
	global_store_dwordx2 v[64:65], v[60:61], off offset:256
	s_nop 1
	v_mov_b64_e32 v[60:61], v[244:245]
	v_mov_b64_e32 v[62:63], v[246:247]
	v_add_f32_e32 v74, v66, v67
	v_pk_fma_f32 v[62:63], v[154:155], v[30:31], v[62:63]
	v_pk_fma_f32 v[60:61], v[156:157], v[28:29], v[60:61]
	global_store_dwordx4 v[68:69], v[60:63], off offset:576
	v_pk_mul_f32 v[72:73], v[44:45], v[60:61]
	v_pk_mul_f32 v[66:67], v[46:47], v[62:63]
	v_mul_f32_e32 v61, v61, v61
	v_fmac_f32_e32 v61, v60, v60
	v_mul_f32_e32 v60, v63, v63
	v_fmac_f32_e32 v60, v62, v62
	v_and_b32_e32 v62, 64, v176
	v_add_f32_e32 v60, v61, v60
	v_xor_b32_e32 v61, 16, v176
	v_add_u32_e32 v62, 64, v62
	v_cmp_lt_i32_e32 vcc, v61, v62
	v_add_f32_e32 v60, v74, v60
	v_cvt_pk_bf16_f32 v72, v72, v73
	v_cvt_pk_bf16_f32 v73, v66, v67
	global_store_dwordx2 v[64:65], v[72:73], off offset:288
	v_cndmask_b32_e32 v61, v176, v61, vcc
	v_lshlrev_b32_e32 v61, 2, v61
	ds_bpermute_b32 v61, v61, v60
	s_waitcnt lgkmcnt(0)
	v_add_f32_e32 v60, v60, v61
	v_xor_b32_e32 v61, 32, v176
	v_cmp_lt_i32_e32 vcc, v61, v62
	s_nop 1
	v_cndmask_b32_e32 v61, v176, v61, vcc
	v_lshlrev_b32_e32 v61, 2, v61
	ds_bpermute_b32 v61, v61, v60
	s_and_saveexec_b64 s[0:1], s[38:39]
	s_cbranch_execz .LBB0_530
	v_lshl_add_u64 v[62:63], v[162:163], 2, s[20:21]
	s_waitcnt lgkmcnt(0)
	v_add_f32_e32 v60, v60, v61
	global_atomic_add_f32 v[62:63], v60, off offset:576

; __device__ __forceinline__ unsigned cvt_pk_bf16(float lo, float hi) { unsigned r; asm volatile("v_cvt_pk_bf16_f32 %0, %1, %2" : "=v"(r) : "v"(lo), "v"(hi)); return r; }
;     __device__ __forceinline__ void operator()(const f32x4 (&acc)[2][2][4][2], const Unit& u, int wr, int wc, int fr, int fq) const {
;     ...
;             for (int m = 0; m < 4; ++m) { const int row = u.pm * BM + ai * HALF + wr * 64 + m * 16 + fr; const size_t off = (size_t)row * ldc + col0;
;                 float ssum = 0.f;
; #pragma unroll
;                 for (int bj = 0; bj < 2; ++bj)
; #pragma unroll
;                     for (int n = 0; n < 2; ++n) { f32x4* p = (f32x4*)(X + off + bj * HALF + n * 16); const f32x4 v = *(const f32x4*)(Xin + off + bj * HALF + n * 16) + acc[ai][bj][m][n] * scale; *p = v;
;                         if (gnext) { ssum += (v.x * v.x + v.y * v.y) + (v.z * v.z + v.w * v.w); const f32x4 o = v * gv[bj][n];
;                             u32x2 w; w.x = cvt_pk_bf16(o.x, o.y); w.y = cvt_pk_bf16(o.z, o.w); *(u32x2*)(XB + off + bj * HALF + n * 16) = w; } }
;                 if (gnext) { ssum += __shfl_xor(ssum, 16); ssum += __shfl_xor(ssum, 32); if (fq == 0) unsafeAtomicAdd(SS + row, ssum); } }
.LBB0_531:
	s_waitcnt lgkmcnt(0)
	s_nop 1
	v_mov_b64_e32 v[60:61], v[236:237]
	v_mov_b64_e32 v[62:63], v[238:239]
	v_mov_b32_e32 v155, v154
	v_pk_fma_f32 v[42:43], v[154:155], v[42:43], v[62:63]
	v_pk_fma_f32 v[40:41], v[156:157], v[40:41], v[60:61]
	global_store_dwordx4 v[68:69], v[40:43], off offset:64
	s_nop 1
	v_mov_b64_e32 v[40:41], v[240:241]
	v_mov_b64_e32 v[42:43], v[242:243]
	v_pk_fma_f32 v[38:39], v[154:155], v[38:39], v[42:43]
	v_pk_fma_f32 v[36:37], v[156:157], v[36:37], v[40:41]
	global_store_dwordx4 v[68:69], v[36:39], off offset:512
	s_nop 1
	v_mov_b64_e32 v[36:37], v[244:245]
	v_mov_b64_e32 v[38:39], v[246:247]
	v_pk_fma_f32 v[30:31], v[154:155], v[30:31], v[38:39]
	v_pk_fma_f32 v[28:29], v[156:157], v[28:29], v[36:37]
	global_store_dwordx4 v[68:69], v[28:31], off offset:576
.LBB0_532:
	s_nop 1
	v_add_u32_e32 v194, 0xa0, v162
	v_ashrrev_i32_e32 v195, 31, v194
	v_lshlrev_b64 v[194:195], 11, v[194:195]
	v_lshl_add_u64 v[194:195], v[194:195], 0, v[164:165]
	v_lshlrev_b64 v[194:195], 2, v[194:195]
	v_lshl_add_u64 v[194:195], s[6:7], 0, v[194:195]
	global_load_dwordx4 v[200:203], v[194:195], off
	global_load_dwordx4 v[204:207], v[194:195], off offset:64
	global_load_dwordx4 v[208:211], v[194:195], off offset:512
	global_load_dwordx4 v[212:215], v[194:195], off offset:576
	v_add_u32_e32 v196, 0xb0, v162
	v_ashrrev_i32_e32 v197, 31, v196
	v_lshlrev_b64 v[196:197], 11, v[196:197]
	v_lshl_add_u64 v[196:197], v[196:197], 0, v[164:165]
	v_lshlrev_b64 v[196:197], 2, v[196:197]
	v_lshl_add_u64 v[196:197], s[6:7], 0, v[196:197]
	global_load_dwordx4 v[216:219], v[196:197], off
	global_load_dwordx4 v[220:223], v[196:197], off offset:64
	global_load_dwordx4 v[224:227], v[196:197], off offset:512
	global_load_dwordx4 v[228:231], v[196:197], off offset:576
	s_waitcnt vmcnt(0)
	v_add_u32_e32 v28, 0xa0, v162
	v_ashrrev_i32_e32 v29, 31, v28
	v_lshlrev_b64 v[28:29], 11, v[28:29]
	v_lshl_add_u64 v[40:41], v[28:29], 0, v[164:165]
	v_lshlrev_b64 v[36:37], 2, v[40:41]
	v_lshl_add_u64 v[38:39], s[6:7], 0, v[36:37]
	s_nop 1
	v_mov_b64_e32 v[28:29], v[200:201]
	v_mov_b64_e32 v[30:31], v[202:203]
	v_mov_b32_e32 v155, v154
	v_lshl_add_u64 v[36:37], s[16:17], 0, v[36:37]
	s_and_b64 vcc, exec, s[42:43]
	v_pk_fma_f32 v[30:31], v[154:155], v[34:35], v[30:31]
	v_pk_fma_f32 v[28:29], v[156:157], v[32:33], v[28:29]
	global_store_dwordx4 v[36:37], v[28:31], off
	s_cbranch_vccnz .LBB0_551
	v_mul_f32_e32 v32, v29, v29
	v_mul_f32_e32 v33, v31, v31
	v_fmac_f32_e32 v32, v28, v28
	v_fmac_f32_e32 v33, v30, v30
	v_add_f32_e32 v34, v32, v33
	v_pk_mul_f32 v[28:29], v[56:57], v[28:29]
	v_lshl_add_u64 v[32:33], v[40:41], 1, s[10:11]
	v_pk_mul_f32 v[30:31], v[58:59], v[30:31]
	v_cvt_pk_bf16_f32 v28, v28, v29
	s_nop 0
	v_cvt_pk_bf16_f32 v29, v30, v31
	global_store_dwordx2 v[32:33], v[28:29], off
	s_nop 1
	v_mov_b64_e32 v[28:29], v[204:205]
	v_mov_b64_e32 v[30:31], v[206:207]
	v_pk_fma_f32 v[28:29], v[156:157], v[24:25], v[28:29]
	v_pk_fma_f32 v[30:31], v[154:155], v[26:27], v[30:31]
	v_mul_f32_e32 v35, v29, v29
	global_store_dwordx4 v[36:37], v[28:31], off offset:64
	v_fmac_f32_e32 v35, v28, v28
	v_mul_f32_e32 v40, v31, v31
	v_pk_mul_f32 v[28:29], v[48:49], v[28:29]
	v_fmac_f32_e32 v40, v30, v30
	v_pk_mul_f32 v[30:31], v[50:51], v[30:31]
	v_cvt_pk_bf16_f32 v28, v28, v29
	v_add_f32_e32 v35, v35, v40
	v_cvt_pk_bf16_f32 v29, v30, v31
	global_store_dwordx2 v[32:33], v[28:29], off offset:32
	s_nop 1
	v_mov_b64_e32 v[28:29], v[208:209]
	v_mov_b64_e32 v[30:31], v[210:211]
	v_add_f32_e32 v34, v34, v35
	v_pk_fma_f32 v[28:29], v[156:157], v[20:21], v[28:29]
	v_pk_fma_f32 v[30:31], v[154:155], v[22:23], v[30:31]
	v_mul_f32_e32 v35, v29, v29
	global_store_dwordx4 v[36:37], v[28:31], off offset:512
	v_fmac_f32_e32 v35, v28, v28
	v_mul_f32_e32 v40, v31, v31
	v_pk_mul_f32 v[28:29], v[52:53], v[28:29]
	v_fmac_f32_e32 v40, v30, v30
	v_pk_mul_f32 v[30:31], v[54:55], v[30:31]
	v_cvt_pk_bf16_f32 v28, v28, v29
	v_add_f32_e32 v35, v35, v40
	v_cvt_pk_bf16_f32 v29, v30, v31
	global_store_dwordx2 v[32:33], v[28:29], off offset:256
	s_nop 1
	v_mov_b64_e32 v[28:29], v[212:213]
	v_mov_b64_e32 v[30:31], v[214:215]
	v_add_f32_e32 v42, v34, v35
	v_pk_fma_f32 v[30:31], v[154:155], v[14:15], v[30:31]
	v_pk_fma_f32 v[28:29], v[156:157], v[12:13], v[28:29]
	global_store_dwordx4 v[36:37], v[28:31], off offset:576
	v_pk_mul_f32 v[40:41], v[44:45], v[28:29]
	v_pk_mul_f32 v[34:35], v[46:47], v[30:31]
	v_mul_f32_e32 v29, v29, v29
	v_fmac_f32_e32 v29, v28, v28
	v_mul_f32_e32 v28, v31, v31
	v_fmac_f32_e32 v28, v30, v30
	v_and_b32_e32 v30, 64, v176
	v_add_f32_e32 v28, v29, v28
	v_xor_b32_e32 v29, 16, v176
	v_add_u32_e32 v30, 64, v30
	v_cmp_lt_i32_e32 vcc, v29, v30
	v_add_f32_e32 v28, v42, v28
	v_cvt_pk_bf16_f32 v40, v40, v41
	v_cvt_pk_bf16_f32 v41, v34, v35
	global_store_dwordx2 v[32:33], v[40:41], off offset:288
	v_cndmask_b32_e32 v29, v176, v29, vcc
	v_lshlrev_b32_e32 v29, 2, v29
	ds_bpermute_b32 v29, v29, v28
	s_waitcnt lgkmcnt(0)
	v_add_f32_e32 v28, v28, v29
	v_xor_b32_e32 v29, 32, v176
	v_cmp_lt_i32_e32 vcc, v29, v30
	s_nop 1
	v_cndmask_b32_e32 v29, v176, v29, vcc
	v_lshlrev_b32_e32 v29, 2, v29
	ds_bpermute_b32 v29, v29, v28
	s_and_saveexec_b64 s[0:1], s[38:39]
	s_cbranch_execz .LBB0_535
	v_lshl_add_u64 v[30:31], v[162:163], 2, s[20:21]
	s_waitcnt lgkmcnt(0)
	v_add_f32_e32 v28, v28, v29
	global_atomic_add_f32 v[30:31], v28, off offset:640

; __device__ __forceinline__ unsigned cvt_pk_bf16(float lo, float hi) { unsigned r; asm volatile("v_cvt_pk_bf16_f32 %0, %1, %2" : "=v"(r) : "v"(lo), "v"(hi)); return r; }
;     __device__ __forceinline__ void operator()(const f32x4 (&acc)[2][2][4][2], const Unit& u, int wr, int wc, int fr, int fq) const {
;     ...
;             for (int m = 0; m < 4; ++m) { const int row = u.pm * BM + ai * HALF + wr * 64 + m * 16 + fr; const size_t off = (size_t)row * ldc + col0;
;                 float ssum = 0.f;
; #pragma unroll
;                 for (int bj = 0; bj < 2; ++bj)
; #pragma unroll
;                     for (int n = 0; n < 2; ++n) { f32x4* p = (f32x4*)(X + off + bj * HALF + n * 16); const f32x4 v = *(const f32x4*)(Xin + off + bj * HALF + n * 16) + acc[ai][bj][m][n] * scale; *p = v;
;                         if (gnext) { ssum += (v.x * v.x + v.y * v.y) + (v.z * v.z + v.w * v.w); const f32x4 o = v * gv[bj][n];
;                             u32x2 w; w.x = cvt_pk_bf16(o.x, o.y); w.y = cvt_pk_bf16(o.z, o.w); *(u32x2*)(XB + off + bj * HALF + n * 16) = w; } }
;                 if (gnext) { ssum += __shfl_xor(ssum, 16); ssum += __shfl_xor(ssum, 32); if (fq == 0) unsafeAtomicAdd(SS + row, ssum); } }
.LBB0_536:
	s_waitcnt lgkmcnt(0)
	s_nop 1
	v_mov_b64_e32 v[28:29], v[204:205]
	v_mov_b64_e32 v[30:31], v[206:207]
	v_mov_b32_e32 v155, v154
	v_pk_fma_f32 v[26:27], v[154:155], v[26:27], v[30:31]
	v_pk_fma_f32 v[24:25], v[156:157], v[24:25], v[28:29]
	global_store_dwordx4 v[36:37], v[24:27], off offset:64
	s_nop 1
	v_mov_b64_e32 v[24:25], v[208:209]
	v_mov_b64_e32 v[26:27], v[210:211]
	v_pk_fma_f32 v[22:23], v[154:155], v[22:23], v[26:27]
	v_pk_fma_f32 v[20:21], v[156:157], v[20:21], v[24:25]
	global_store_dwordx4 v[36:37], v[20:23], off offset:512
	s_nop 1
	v_mov_b64_e32 v[20:21], v[212:213]
	v_mov_b64_e32 v[22:23], v[214:215]
	v_pk_fma_f32 v[14:15], v[154:155], v[14:15], v[22:23]
	v_pk_fma_f32 v[12:13], v[156:157], v[12:13], v[20:21]
	global_store_dwordx4 v[36:37], v[12:15], off offset:576
.LBB0_537:
	s_nop 1
	v_add_u32_e32 v12, 0xb0, v162
	v_ashrrev_i32_e32 v13, 31, v12
	v_lshlrev_b64 v[12:13], 11, v[12:13]
	v_lshl_add_u64 v[24:25], v[12:13], 0, v[164:165]
	v_lshlrev_b64 v[20:21], 2, v[24:25]
	v_lshl_add_u64 v[22:23], s[6:7], 0, v[20:21]
	s_nop 1
	v_mov_b64_e32 v[12:13], v[216:217]
	v_mov_b64_e32 v[14:15], v[218:219]
	v_mov_b32_e32 v155, v154
	v_lshl_add_u64 v[20:21], s[16:17], 0, v[20:21]
	s_and_b64 vcc, exec, s[42:43]
	v_pk_fma_f32 v[14:15], v[154:155], v[18:19], v[14:15]
	v_pk_fma_f32 v[12:13], v[156:157], v[16:17], v[12:13]
	global_store_dwordx4 v[20:21], v[12:15], off
	s_cbranch_vccnz .LBB0_552
	v_pk_mul_f32 v[18:19], v[56:57], v[12:13]
	v_lshl_add_u64 v[32:33], v[24:25], 1, s[10:11]
	v_pk_mul_f32 v[16:17], v[58:59], v[14:15]
	v_cvt_pk_bf16_f32 v18, v18, v19
	v_mul_f32_e32 v13, v13, v13
	v_cvt_pk_bf16_f32 v19, v16, v17
	global_store_dwordx2 v[32:33], v[18:19], off
	s_nop 1
	v_mov_b64_e32 v[16:17], v[220:221]
	v_mov_b64_e32 v[18:19], v[222:223]
	v_and_b32_e32 v35, 64, v176
	v_xor_b32_e32 v34, 16, v176
	v_fmac_f32_e32 v13, v12, v12
	v_add_u32_e32 v12, 64, v35
	v_mul_f32_e32 v15, v15, v15
	v_cmp_lt_i32_e32 vcc, v34, v12
	v_fmac_f32_e32 v15, v14, v14
	v_add_f32_e32 v13, v13, v15
	v_cndmask_b32_e32 v14, v176, v34, vcc
	v_lshlrev_b32_e32 v34, 2, v14
	v_xor_b32_e32 v36, 32, v176
	v_cmp_lt_i32_e32 vcc, v36, v12
	v_pk_fma_f32 v[16:17], v[156:157], v[8:9], v[16:17]
	v_pk_fma_f32 v[18:19], v[154:155], v[10:11], v[18:19]
	v_pk_mul_f32 v[26:27], v[48:49], v[16:17]
	global_store_dwordx4 v[20:21], v[16:19], off offset:64
	v_pk_mul_f32 v[24:25], v[50:51], v[18:19]
	v_cvt_pk_bf16_f32 v26, v26, v27
	v_mul_f32_e32 v14, v17, v17
	v_cvt_pk_bf16_f32 v27, v24, v25
	global_store_dwordx2 v[32:33], v[26:27], off offset:32
	s_nop 1
	v_mov_b64_e32 v[24:25], v[224:225]
	v_mov_b64_e32 v[26:27], v[226:227]
	v_mul_f32_e32 v15, v19, v19
	v_fmac_f32_e32 v14, v16, v16
	v_fmac_f32_e32 v15, v18, v18
	v_add_f32_e32 v14, v14, v15
	v_add_f32_e32 v13, v13, v14
	v_pk_fma_f32 v[24:25], v[156:157], v[4:5], v[24:25]
	v_pk_fma_f32 v[26:27], v[154:155], v[6:7], v[26:27]
	v_pk_mul_f32 v[30:31], v[52:53], v[24:25]
	global_store_dwordx4 v[20:21], v[24:27], off offset:512
	s_waitcnt lgkmcnt(0)
	v_pk_mul_f32 v[28:29], v[54:55], v[26:27]
	v_cvt_pk_bf16_f32 v30, v30, v31
	v_mul_f32_e32 v14, v25, v25
	v_cvt_pk_bf16_f32 v31, v28, v29
	global_store_dwordx2 v[32:33], v[30:31], off offset:256
	s_nop 1
	v_mov_b64_e32 v[28:29], v[228:229]
	v_mov_b64_e32 v[30:31], v[230:231]
	v_mul_f32_e32 v15, v27, v27
	v_fmac_f32_e32 v14, v24, v24
	v_fmac_f32_e32 v15, v26, v26
	v_add_f32_e32 v14, v14, v15
	v_add_f32_e32 v13, v13, v14
	v_pk_fma_f32 v[16:17], v[154:155], v[2:3], v[30:31]
	v_pk_fma_f32 v[14:15], v[156:157], v[0:1], v[28:29]
	v_mul_f32_e32 v19, v17, v17
	v_mul_f32_e32 v18, v15, v15
	v_fmac_f32_e32 v18, v14, v14
	v_fmac_f32_e32 v19, v16, v16
	v_add_f32_e32 v18, v18, v19
	v_add_f32_e32 v13, v13, v18
	ds_bpermute_b32 v18, v34, v13
	v_cndmask_b32_e32 v19, v176, v36, vcc
	global_store_dwordx4 v[20:21], v[14:17], off offset:576
	s_waitcnt lgkmcnt(0)
	v_add_f32_e32 v12, v13, v18
	v_lshlrev_b32_e32 v13, 2, v19
	ds_bpermute_b32 v13, v13, v12
	v_pk_mul_f32 v[14:15], v[44:45], v[14:15]
	v_pk_mul_f32 v[16:17], v[46:47], v[16:17]
	v_cvt_pk_bf16_f32 v14, v14, v15
	s_nop 0
	v_cvt_pk_bf16_f32 v15, v16, v17
	global_store_dwordx2 v[32:33], v[14:15], off offset:288
	s_and_saveexec_b64 s[0:1], s[38:39]
	s_cbranch_execz .LBB0_540
	v_lshl_add_u64 v[14:15], v[162:163], 2, s[20:21]
	s_waitcnt lgkmcnt(0)
	v_add_f32_e32 v12, v12, v13
	global_atomic_add_f32 v[14:15], v12, off offset:704

; __device__ __forceinline__ unsigned cvt_pk_bf16(float lo, float hi) { unsigned r; asm volatile("v_cvt_pk_bf16_f32 %0, %1, %2" : "=v"(r) : "v"(lo), "v"(hi)); return r; }
;     __device__ __forceinline__ void operator()(const f32x4 (&acc)[2][2][4][2], const Unit& u, int wr, int wc, int fr, int fq) const {
;     ...
;             for (int m = 0; m < 4; ++m) { const int row = u.pm * BM + ai * HALF + wr * 64 + m * 16 + fr; const size_t off = (size_t)row * ldc + col0;
;                 float ssum = 0.f;
; #pragma unroll
;                 for (int bj = 0; bj < 2; ++bj)
; #pragma unroll
;                     for (int n = 0; n < 2; ++n) { f32x4* p = (f32x4*)(X + off + bj * HALF + n * 16); const f32x4 v = *(const f32x4*)(Xin + off + bj * HALF + n * 16) + acc[ai][bj][m][n] * scale; *p = v;
;                         if (gnext) { ssum += (v.x * v.x + v.y * v.y) + (v.z * v.z + v.w * v.w); const f32x4 o = v * gv[bj][n];
;                             u32x2 w; w.x = cvt_pk_bf16(o.x, o.y); w.y = cvt_pk_bf16(o.z, o.w); *(u32x2*)(XB + off + bj * HALF + n * 16) = w; } }
;                 if (gnext) { ssum += __shfl_xor(ssum, 16); ssum += __shfl_xor(ssum, 32); if (fq == 0) unsafeAtomicAdd(SS + row, ssum); } }
.LBB0_541:
	s_waitcnt lgkmcnt(0)
	s_nop 1
	v_mov_b64_e32 v[12:13], v[220:221]
	v_mov_b64_e32 v[14:15], v[222:223]
	v_mov_b32_e32 v155, v154
	v_pk_fma_f32 v[10:11], v[154:155], v[10:11], v[14:15]
	v_pk_fma_f32 v[8:9], v[156:157], v[8:9], v[12:13]
	global_store_dwordx4 v[20:21], v[8:11], off offset:64
	s_nop 1
	v_mov_b64_e32 v[8:9], v[224:225]
	v_mov_b64_e32 v[10:11], v[226:227]
	v_pk_fma_f32 v[6:7], v[154:155], v[6:7], v[10:11]
	v_pk_fma_f32 v[4:5], v[156:157], v[4:5], v[8:9]
	global_store_dwordx4 v[20:21], v[4:7], off offset:512
	s_nop 1
	v_mov_b64_e32 v[4:5], v[228:229]
	v_mov_b64_e32 v[6:7], v[230:231]
	v_pk_fma_f32 v[2:3], v[154:155], v[2:3], v[6:7]
	v_pk_fma_f32 v[0:1], v[156:157], v[0:1], v[4:5]
	global_store_dwordx4 v[20:21], v[0:3], off offset:576

; #define LAS __attribute__((address_space(3)))
; __device__ __forceinline__ void rw_scan4(const int tid, LAS float* lds, const float* RW, int task, int ntasks, int mode, const float* SIN, float* PQ, float* Y) {
;     ...
;     __syncthreads();
;     if (active) {
; #pragma unroll
;         for (int a = 0; a < 6; ++a) st[a] = *(const f32x4*)(gsrc + a * RWSZ);
; #pragma unroll
;         for (int a = 0; a < 6; ++a) *(LAS f32x4*)(sb + (a * TB + srow) * 64 + sc4 * 4) = st[a];
;     }
;     __syncthreads();
;     for (int b = 0; b < nb; ++b) {
;         if (active && b + 1 < nb) {
; #pragma unroll
;             for (int a = 0; a < 6; ++a) st[a] = *(const f32x4*)(gsrc + a * RWSZ + (size_t)(b + 1) * TB * GW);
;         }
;         if (active) {
;             const LAS float* cur = sb + (b & 1) * (6 * TB * 64);
;             float* yo = Y + (size_t)(t0 + b * TB) * D + 2 * GW + head * 64 + rg * 4;
; #pragma unroll 4
;             for (int tt = 0; tt < TB; ++tt) {
;                 const LAS float* base = cur + tt * 64 + kp * 8;
;                 const f32x4 r0 = *(const LAS f32x4*)(base), r1 = *(const LAS f32x4*)(base + 4);
;                 const f32x4 w0 = *(const LAS f32x4*)(base + TB * 64), w1 = *(const LAS f32x4*)(base + TB * 64 + 4);
;                 const f32x4 k0 = *(const LAS f32x4*)(base + 2 * TB * 64), k1 = *(const LAS f32x4*)(base + 2 * TB * 64 + 4);
;                 const f32x4 a0 = *(const LAS f32x4*)(base + 3 * TB * 64), a1 = *(const LAS f32x4*)(base + 3 * TB * 64 + 4);
;                 const f32x4 b0 = *(const LAS f32x4*)(base + 4 * TB * 64), b1 = *(const LAS f32x4*)(base + 4 * TB * 64 + 4);
;                 f32x4 v4 = (f32x4){0.f, 0.f, 0.f, 0.f};
;                 if (kind != 1) v4 = *(const LAS f32x4*)(cur + (5 * TB + tt) * 64 + rg * 4);
;                 const f32x2 av[4] = {(f32x2){a0.x, a0.y}, (f32x2){a0.z, a0.w}, (f32x2){a1.x, a1.y}, (f32x2){a1.z, a1.w}};
;                 const f32x2 wv[4] = {(f32x2){w0.x, w0.y}, (f32x2){w0.z, w0.w}, (f32x2){w1.x, w1.y}, (f32x2){w1.z, w1.w}};
;                 const f32x2 bv[4] = {(f32x2){b0.x, b0.y}, (f32x2){b0.z, b0.w}, (f32x2){b1.x, b1.y}, (f32x2){b1.z, b1.w}};
;                 const f32x2 kv[4] = {(f32x2){k0.x, k0.y}, (f32x2){k0.z, k0.w}, (f32x2){k1.x, k1.y}, (f32x2){k1.z, k1.w}};
;                 float sa[4];
; #pragma unroll
.LBB0_558:
	v_readlane_b32 s0, v255, 61
	s_cmp_lg_u32 s0, 2
	s_cbranch_scc1 .Lp0_nohook
	v_readlane_b32 s0, v255, 55
	s_cmp_ge_u32 s0, 18
	s_cbranch_scc1 .Lp0_nohook
	s_barrier
	s_add_i32 s0, s0, 1
	s_nop 0
	v_writelane_b32 v255, s0, 55

; __global__ void __launch_bounds__(NTHR, 2) hymba_fwd(Args args) {
;     ...
;             {
;                 float* LT = WSP(float, WS_LORA);
;                 for (int i = bid * NTHR + tid; i < LT_TOTAL; i += G * NTHR) {
;                     const float* src; int N_, K_, o;
;                     if (i < LT_AA) { src = L.rw_wa; N_ = 64; K_ = GW; o = i; } else if (i < LT_GA) { src = L.rw_aa; N_ = 64; K_ = GW; o = i - LT_AA; } else if (i < LT_WB) { src = L.rw_ga; N_ = 128; K_ = GW; o = i - LT_GA; }
;                     else if (i < LT_AB) { src = L.rw_wb; N_ = GW; K_ = 64; o = i - LT_WB; } else if (i < LT_GB) { src = L.rw_ab; N_ = GW; K_ = 64; o = i - LT_AB; } else { src = L.rw_gb; N_ = GW; K_ = 128; o = i - LT_GB; }
;                     const int n_ = o / K_, k_ = o % K_;
;                     LT[i] = src[(size_t)k_ * N_ + n_];
;                 }
;             }
.LBB0_591:
	v_readlane_b32 s0, v255, 61
	s_cmp_eq_u32 s0, 2
	s_cbranch_scc1 .Lgs_drain
	s_cmp_lg_u32 s0, 0
	s_cbranch_scc1 .LBB0_627
	s_waitcnt vmcnt(5)
	v_lshl_add_u32 v32, s44, 9, v148
	s_mov_b32 s0, 0x40000
	v_cmp_gt_i32_e32 vcc, s0, v32
	s_and_saveexec_b64 s[0:1], vcc
	s_cbranch_execz .LBB0_612
	v_readlane_b32 s26, v254, 30
	v_readlane_b32 s27, v254, 31
	s_lshl_b64 s[24:25], s[26:27], 17
	s_waitcnt lgkmcnt(0)
	s_add_u32 s14, s20, s24
	s_addc_u32 s15, s21, s25
	s_add_u32 s20, s22, s24
	s_addc_u32 s21, s23, s25
	s_add_u32 s4, s4, s24
	s_addc_u32 s5, s5, s25
	s_add_u32 s6, s6, s24
	s_addc_u32 s7, s7, s25
	s_lshl_b64 s[22:23], s[26:27], 18
	s_add_u32 s8, s8, s22
	s_addc_u32 s9, s9, s23
	s_add_u32 s10, s10, s22
	s_addc_u32 s11, s11, s23
	s_lshl_b32 s22, s45, 9
	v_ashrrev_i32_e32 v33, 31, v32
	v_lshl_add_u64 v[0:1], v[32:33], 2, s[18:19]
	s_mov_b64 s[24:25], 0x29c00000
	s_ashr_i32 s23, s22, 31
	v_lshl_add_u64 v[0:1], v[0:1], 0, s[24:25]
	s_lshl_b64 s[24:25], s[22:23], 2
	s_mov_b64 s[26:27], 0
	s_waitcnt vmcnt(4)
	v_mov_b32_e32 v6, v32
	s_branch .LBB0_595
